# v18 + nt on phase-6 (post-mixer norm) x loads and h1b/f stores
# speedup vs baseline: 1.0134x; 1.0134x over previous
; __device__ __forceinline__ unsigned pk_bf16(float lo, float hi) { const f32x2 v = {lo, hi}; return __builtin_bit_cast(unsigned, __builtin_convertvector(v, b16x2)); }
;     __device__ __forceinline__ void row(int r, int col32, int fq, const f32x4& a00, const f32x4& a01, const f32x4& a10, const f32x4& a11) const { half(r, col32, fq, a00, a01); half(r, col32 + HALF, fq, a10, a11); }
; __device__ __forceinline__ void phase6(const Params& p) {
;     ...
;     for (int it = blockIdx.x; it < MS / 16; it += gridDim.x) {
;         const int row0 = it * 16 + (threadIdx.x >> 6) * 2;
;         f32x4 v[2][4], x[2][4];
; #pragma unroll
;         for (int r = 0; r < 2; ++r)
; #pragma unroll
;             for (int j = 0; j < 4; ++j) {
;                 { const u32x2 pb2 = *(const u32x2*)((const bf16_t*)(ws + O_P) + (size_t)(row0 + r) * D + 4 * lane + 256 * j);
;                   v[r][j] = (f32x4){__uint_as_float(pb2.x << 16), __uint_as_float(pb2.x & 0xffff0000u), __uint_as_float(pb2.y << 16), __uint_as_float(pb2.y & 0xffff0000u)}; }
;                 x[r][j] = *(const f32x4*)(p.in[0] + (size_t)(row0 + r) * D + 4 * lane + 256 * j);
;             }
; #pragma unroll
;         for (int r = 0; r < 2; ++r) {
;             const int row = row0 + r;
;             float ss = 0.f;
; #pragma unroll
;             for (int j = 0; j < 4; ++j) ss += (v[r][j][0] * v[r][j][0] + v[r][j][1] * v[r][j][1]) + (v[r][j][2] * v[r][j][2] + v[r][j][3] * v[r][j][3]);
;             const float rs = rsqrtf(wave_sum(ss) * (1.0f / D) + RMS_EPS);
;             float s2 = 0.f;
; #pragma unroll
;             for (int j = 0; j < 4; ++j) {
;                 v[r][j] = x[r][j] + v[r][j] * rs * g1[j];
;                 { u32x2 hb; hb.x = pk_bf16(v[r][j][0], v[r][j][1]); hb.y = pk_bf16(v[r][j][2], v[r][j][3]);
;                   *(u32x2*)((bf16_t*)(ws + O_H1B) + (size_t)row * D + 4 * lane + 256 * j) = hb;
;                   v[r][j] = (f32x4){__uint_as_float(hb.x << 16), __uint_as_float(hb.x & 0xffff0000u), __uint_as_float(hb.y << 16), __uint_as_float(hb.y & 0xffff0000u)}; }
;                 s2 += (v[r][j][0] * v[r][j][0] + v[r][j][1] * v[r][j][1]) + (v[r][j][2] * v[r][j][2] + v[r][j][3] * v[r][j][3]);
;             }
;             const float rs2 = rsqrtf(wave_sum(s2) * (1.0f / D) + RMS_EPS);
.LBB0_1184:
	v_ashrrev_i32_e32 v49, 31, v48
	v_lshlrev_b64 v[54:55], 11, v[48:49]
	v_lshl_add_u64 v[32:33], v[40:41], 0, v[54:55]
	global_load_dwordx2 v[34:35], v[32:33], off offset:1536
	global_load_dwordx2 v[36:37], v[32:33], off
	global_load_dwordx2 v[38:39], v[32:33], off offset:512
	global_load_dwordx2 v[56:57], v[32:33], off offset:1024
	v_add_u32_e32 v32, 1, v48
	v_ashrrev_i32_e32 v33, 31, v32
	v_lshlrev_b64 v[52:53], 11, v[32:33]
	v_lshl_add_u64 v[58:59], v[40:41], 0, v[52:53]
	global_load_dwordx2 v[86:87], v[58:59], off offset:1536
	v_lshlrev_b64 v[60:61], 12, v[48:49]
	v_lshl_add_u64 v[60:61], v[46:47], 0, v[60:61]
	global_load_dwordx4 v[62:65], v[60:61], off nt
	global_load_dwordx4 v[66:69], v[60:61], off offset:1024 nt
	global_load_dwordx4 v[70:73], v[60:61], off offset:2048 nt
	global_load_dwordx4 v[82:85], v[60:61], off offset:3072 nt
	global_load_dwordx2 v[106:107], v[58:59], off
	global_load_dwordx2 v[108:109], v[58:59], off offset:512
	global_load_dwordx2 v[110:111], v[58:59], off offset:1024
	v_lshlrev_b64 v[32:33], 12, v[32:33]
	s_add_i32 s7, s7, s92
	s_cmpk_lt_i32 s7, 0x800
	v_add_u32_e32 v48, s1, v48
	s_waitcnt vmcnt(11)
	v_lshlrev_b32_e32 v89, 16, v34
	s_waitcnt vmcnt(10)
	v_and_b32_e32 v95, 0xffff0000, v36
	v_and_b32_e32 v97, 0xffff0000, v37
	v_and_b32_e32 v91, 0xffff0000, v34
	v_lshlrev_b32_e32 v92, 16, v35
	v_and_b32_e32 v93, 0xffff0000, v35
	v_lshlrev_b32_e32 v94, 16, v36
	v_lshlrev_b32_e32 v96, 16, v37
	s_waitcnt vmcnt(9)
	v_lshlrev_b32_e32 v98, 16, v38
	v_and_b32_e32 v101, 0xffff0000, v39
	v_and_b32_e32 v100, 0xffff0000, v38
	v_mul_f32_e32 v34, v97, v97
	v_mul_f32_e32 v38, v95, v95
	v_mov_b32_e32 v35, v89
	v_lshlrev_b32_e32 v99, 16, v39
	s_waitcnt vmcnt(8)
	v_and_b32_e32 v103, 0xffff0000, v56
	v_and_b32_e32 v105, 0xffff0000, v57
	v_pk_mul_f32 v[36:37], v[100:101], v[100:101]
	v_pk_fma_f32 v[74:75], v[96:97], v[96:97], v[34:35] op_sel_hi:[1,1,0]
	v_pk_fma_f32 v[38:39], v[94:95], v[94:95], v[38:39] op_sel_hi:[1,1,0]
	v_lshlrev_b32_e32 v102, 16, v56
	v_lshlrev_b32_e32 v104, 16, v57
	v_mul_f32_e32 v56, v103, v103
	v_mul_f32_e32 v60, v105, v105
	v_pk_fma_f32 v[36:37], v[98:99], v[98:99], v[36:37]
	v_mov_b32_e32 v88, v38
	v_mov_b32_e32 v34, v74
	v_mul_f32_e32 v49, v91, v91
	v_mul_f32_e32 v81, v92, v92
	v_mul_f32_e32 v90, v93, v93
	v_pk_fma_f32 v[56:57], v[102:103], v[102:103], v[56:57] op_sel_hi:[1,1,0]
	v_pk_fma_f32 v[60:61], v[104:105], v[104:105], v[60:61] op_sel_hi:[1,1,0]
	v_pk_add_f32 v[38:39], v[38:39], v[74:75]
	v_pk_add_f32 v[36:37], v[36:37], v[36:37] op_sel:[0,1] op_sel_hi:[1,0]
	v_pk_mul_f32 v[34:35], v[88:89], v[34:35]
	v_mov_b32_e32 v57, v81
	v_mov_b32_e32 v61, v90
	v_mov_b32_e32 v37, v49
	v_mov_b32_e32 v39, v35
	v_pk_add_f32 v[56:57], v[56:57], v[60:61]
	v_pk_add_f32 v[34:35], v[38:39], v[36:37]
	s_waitcnt vmcnt(7)
	v_lshlrev_b32_e32 v59, 16, v86
	v_pk_add_f32 v[34:35], v[34:35], v[56:57]
	v_and_b32_e32 v61, 0xffff0000, v86
	v_add_f32_e32 v34, v34, v35
	ds_bpermute_b32 v35, v51, v34
	v_and_b32_e32 v57, 0xffff0000, v87
	v_mov_b32_e32 v86, v98
	v_mov_b32_e32 v90, v89
	v_mov_b32_e32 v115, v59
	s_waitcnt lgkmcnt(0)
	v_add_f32_e32 v34, v34, v35
	ds_bpermute_b32 v35, v76, v34
	s_waitcnt vmcnt(0)
	v_and_b32_e32 v113, 0xffff0000, v110
	v_lshlrev_b32_e32 v112, 16, v110
	v_lshlrev_b32_e32 v110, 16, v111
	v_and_b32_e32 v111, 0xffff0000, v111
	s_waitcnt lgkmcnt(0)
	v_add_f32_e32 v34, v34, v35
	ds_bpermute_b32 v35, v77, v34
	v_mul_f32_e32 v81, v57, v57
	v_lshl_add_u64 v[74:75], v[46:47], 0, v[32:33]
	s_waitcnt lgkmcnt(0)
	v_add_f32_e32 v34, v34, v35
	ds_bpermute_b32 v35, v78, v34
	s_waitcnt lgkmcnt(0)
	v_add_f32_e32 v49, v34, v35
	ds_bpermute_b32 v56, v79, v49
	global_load_dwordx4 v[36:39], v[74:75], off nt
	global_load_dwordx4 v[32:35], v[74:75], off offset:1024 nt
	s_waitcnt lgkmcnt(0)
	v_add_f32_e32 v49, v49, v56
	ds_bpermute_b32 v58, v80, v49
	v_lshlrev_b32_e32 v56, 16, v87
	v_mov_b32_e32 v87, v100
	v_mov_b32_e32 v100, v99
	v_mul_f32_e32 v60, v56, v56
	s_waitcnt lgkmcnt(0)
	v_add_f32_e32 v49, v49, v58
	v_fmamk_f32 v49, v49, 0x3a800000, v50
	v_mul_f32_e32 v58, 0x4b800000, v49
	v_cmp_gt_f32_e32 vcc, s6, v49
	s_nop 1
	v_cndmask_b32_e32 v49, v49, v58, vcc
	v_rsq_f32_e32 v49, v49
	s_nop 0
	v_mul_f32_e32 v58, 0x45800000, v49
	v_cndmask_b32_e32 v58, v49, v58, vcc
	v_pk_mul_f32 v[88:89], v[58:59], v[94:95] op_sel_hi:[0,1]
	v_pk_mul_f32 v[94:95], v[58:59], v[96:97] op_sel_hi:[0,1]
	v_pk_mul_f32 v[86:87], v[58:59], v[86:87] op_sel_hi:[0,1]
	v_pk_mul_f32 v[96:97], v[58:59], v[100:101] op_sel_hi:[0,1]
	v_pk_mul_f32 v[90:91], v[58:59], v[90:91] op_sel_hi:[0,1]
	v_pk_mul_f32 v[92:93], v[58:59], v[92:93] op_sel_hi:[0,1]
	v_pk_fma_f32 v[64:65], v[2:3], v[94:95], v[64:65]
	v_pk_fma_f32 v[62:63], v[0:1], v[88:89], v[62:63]
	v_pk_fma_f32 v[68:69], v[6:7], v[96:97], v[68:69]
	v_pk_fma_f32 v[66:67], v[4:5], v[86:87], v[66:67]
	v_pk_mul_f32 v[98:99], v[58:59], v[102:103] op_sel_hi:[0,1]
	v_pk_mul_f32 v[100:101], v[58:59], v[104:105] op_sel_hi:[0,1]
	v_pk_fma_f32 v[84:85], v[14:15], v[92:93], v[84:85]
	v_pk_fma_f32 v[82:83], v[12:13], v[90:91], v[82:83]
	v_cvt_pk_bf16_f32 v90, v62, v63
	v_cvt_pk_bf16_f32 v91, v64, v65
	v_cvt_pk_bf16_f32 v92, v66, v67
	v_cvt_pk_bf16_f32 v93, v68, v69
	v_pk_fma_f32 v[72:73], v[10:11], v[100:101], v[72:73]
	v_pk_fma_f32 v[70:71], v[8:9], v[98:99], v[70:71]
	v_and_b32_e32 v99, 0xffff0000, v91
	v_and_b32_e32 v101, 0xffff0000, v90
	v_and_b32_e32 v63, 0xffff0000, v93
	v_and_b32_e32 v67, 0xffff0000, v92
	v_cvt_pk_bf16_f32 v94, v70, v71
	v_cvt_pk_bf16_f32 v96, v82, v83
	v_lshlrev_b32_e32 v98, 16, v91
	v_lshlrev_b32_e32 v100, 16, v90
	v_lshlrev_b32_e32 v62, 16, v93
	v_lshlrev_b32_e32 v66, 16, v92
; __device__ __forceinline__ unsigned pk_bf16(float lo, float hi) { const f32x2 v = {lo, hi}; return __builtin_bit_cast(unsigned, __builtin_convertvector(v, b16x2)); }
;     __device__ __forceinline__ void row(int r, int col32, int fq, const f32x4& a00, const f32x4& a01, const f32x4& a10, const f32x4& a11) const { half(r, col32, fq, a00, a01); half(r, col32 + HALF, fq, a10, a11); }
;     __device__ __forceinline__ void row(int r, int col32, int fq, const f32x4& a00, const f32x4& a01, const f32x4& a10, const f32x4& a11) const { half(r, col32, fq, a00, a01); half(r, col32 + HALF, fq, a10, a11); }
;     __device__ __forceinline__ void row(int r, int col32, int fq, const f32x4& a00, const f32x4& a01, const f32x4& a10, const f32x4& a11) const { half(r, col32, fq, a00, a01); half(r, col32 + HALF, fq, a10, a11); }
; __device__ __forceinline__ void phase6(const Params& p) {
;     ...
;         for (int r = 0; r < 2; ++r) {
;             const int row = row0 + r;
;             float ss = 0.f;
; #pragma unroll
;             for (int j = 0; j < 4; ++j) ss += (v[r][j][0] * v[r][j][0] + v[r][j][1] * v[r][j][1]) + (v[r][j][2] * v[r][j][2] + v[r][j][3] * v[r][j][3]);
;             const float rs = rsqrtf(wave_sum(ss) * (1.0f / D) + RMS_EPS);
;             float s2 = 0.f;
; #pragma unroll
;             for (int j = 0; j < 4; ++j) {
;                 v[r][j] = x[r][j] + v[r][j] * rs * g1[j];
;                 { u32x2 hb; hb.x = pk_bf16(v[r][j][0], v[r][j][1]); hb.y = pk_bf16(v[r][j][2], v[r][j][3]);
;                   *(u32x2*)((bf16_t*)(ws + O_H1B) + (size_t)row * D + 4 * lane + 256 * j) = hb;
;                   v[r][j] = (f32x4){__uint_as_float(hb.x << 16), __uint_as_float(hb.x & 0xffff0000u), __uint_as_float(hb.y << 16), __uint_as_float(hb.y & 0xffff0000u)}; }
;                 s2 += (v[r][j][0] * v[r][j][0] + v[r][j][1] * v[r][j][1]) + (v[r][j][2] * v[r][j][2] + v[r][j][3] * v[r][j][3]);
;             }
;             const float rs2 = rsqrtf(wave_sum(s2) * (1.0f / D) + RMS_EPS);
;             bf16_t* fr_ = (bf16_t*)(ws + O_F) + (size_t)row * D;
; #pragma unroll
;             for (int j = 0; j < 4; ++j) {
;                 u32x2 w; w.x = pk_bf16(v[r][j][0] * rs2 * g2[j][0], v[r][j][1] * rs2 * g2[j][1]); w.y = pk_bf16(v[r][j][2] * rs2 * g2[j][2], v[r][j][3] * rs2 * g2[j][3]);
;                 *(u32x2*)(fr_ + 4 * lane + 256 * j) = w;
;             }
	v_mov_b32_e32 v70, v101
	v_mov_b32_e32 v71, v99
	v_mov_b32_e32 v82, v67
	v_mov_b32_e32 v83, v63
	v_cvt_pk_bf16_f32 v95, v72, v73
	v_mov_b32_e32 v68, v100
	v_mov_b32_e32 v69, v98
	v_mov_b32_e32 v72, v66
	v_mov_b32_e32 v73, v62
	v_pk_mul_f32 v[70:71], v[70:71], v[70:71]
	v_pk_mul_f32 v[82:83], v[82:83], v[82:83]
	v_lshlrev_b32_e32 v64, 16, v95
	v_pk_fma_f32 v[68:69], v[68:69], v[68:69], v[70:71]
	v_pk_fma_f32 v[70:71], v[72:73], v[72:73], v[82:83]
	v_cvt_pk_bf16_f32 v97, v84, v85
	v_and_b32_e32 v65, 0xffff0000, v95
	v_mul_f32_e32 v58, v64, v64
	v_pk_add_f32 v[86:87], v[70:71], v[70:71] op_sel_hi:[0,1]
	v_lshlrev_b32_e32 v70, 16, v94
	v_pk_fma_f32 v[84:85], v[64:65], v[64:65], v[58:59] op_sel_hi:[1,1,0]
	v_pk_add_f32 v[82:83], v[68:69], v[68:69] op_sel_hi:[0,1]
	v_and_b32_e32 v71, 0xffff0000, v94
	v_mul_f32_e32 v58, v70, v70
	v_lshlrev_b32_e32 v68, 16, v97
	v_and_b32_e32 v69, 0xffff0000, v97
	v_lshlrev_b32_e32 v72, 16, v96
	v_and_b32_e32 v73, 0xffff0000, v96
	v_pk_fma_f32 v[88:89], v[70:71], v[70:71], v[58:59] op_sel_hi:[1,1,0]
	v_pk_mul_f32 v[102:103], v[68:69], v[68:69]
	v_pk_mul_f32 v[104:105], v[72:73], v[72:73]
	v_mov_b32_e32 v82, v102
	v_mov_b32_e32 v86, v103
	v_mov_b32_e32 v88, v104
	v_mov_b32_e32 v84, v105
	v_and_b32_e32 v105, 0xffff0000, v107
	v_pk_add_f32 v[82:83], v[82:83], v[86:87]
	v_pk_add_f32 v[84:85], v[88:89], v[84:85]
	v_and_b32_e32 v103, 0xffff0000, v106
	v_lshlrev_b32_e32 v104, 16, v107
	v_mul_f32_e32 v58, v105, v105
	v_pk_add_f32 v[82:83], v[84:85], v[82:83]
	v_lshlrev_b32_e32 v102, 16, v106
	v_pk_fma_f32 v[84:85], v[104:105], v[104:105], v[58:59] op_sel_hi:[1,1,0]
	v_lshlrev_b32_e32 v107, 16, v109
	v_lshlrev_b32_e32 v106, 16, v108
	v_and_b32_e32 v109, 0xffff0000, v109
	v_and_b32_e32 v108, 0xffff0000, v108
	v_mul_f32_e32 v58, v103, v103
	v_pk_mul_f32 v[86:87], v[108:109], v[108:109]
	v_pk_fma_f32 v[88:89], v[102:103], v[102:103], v[58:59] op_sel_hi:[1,1,0]
	v_pk_fma_f32 v[86:87], v[106:107], v[106:107], v[86:87]
	v_mov_b32_e32 v58, v88
	v_mov_b32_e32 v114, v84
	v_mul_f32_e32 v49, v61, v61
	v_pk_add_f32 v[84:85], v[88:89], v[84:85]
	v_pk_mul_f32 v[88:89], v[58:59], v[114:115]
	v_pk_add_f32 v[86:87], v[86:87], v[86:87] op_sel:[0,1] op_sel_hi:[1,0]
	v_mov_b32_e32 v85, v89
	v_mov_b32_e32 v87, v49
	v_mul_f32_e32 v58, v113, v113
	v_pk_add_f32 v[84:85], v[84:85], v[86:87]
	v_pk_fma_f32 v[86:87], v[112:113], v[112:113], v[58:59] op_sel_hi:[1,1,0]
	v_mul_f32_e32 v58, v111, v111
	v_pk_fma_f32 v[88:89], v[110:111], v[110:111], v[58:59] op_sel_hi:[1,1,0]
	v_mov_b32_e32 v87, v60
	v_mov_b32_e32 v89, v81
	v_pk_add_f32 v[86:87], v[86:87], v[88:89]
	s_nop 0
	v_pk_add_f32 v[84:85], v[84:85], v[86:87]
	v_mov_b32_e32 v87, v82
	v_mov_b32_e32 v86, v84
	v_mov_b32_e32 v82, v85
	v_pk_add_f32 v[86:87], v[86:87], v[82:83]
	ds_bpermute_b32 v89, v51, v87
	ds_bpermute_b32 v88, v51, v86
	global_load_dwordx4 v[82:85], v[74:75], off offset:2048 nt
	s_waitcnt lgkmcnt(0)
	v_pk_add_f32 v[114:115], v[86:87], v[88:89]
	global_load_dwordx4 v[86:89], v[74:75], off offset:3072 nt
	ds_bpermute_b32 v117, v76, v115
	ds_bpermute_b32 v116, v76, v114
	s_waitcnt lgkmcnt(0)
	v_pk_add_f32 v[74:75], v[114:115], v[116:117]
	ds_bpermute_b32 v115, v77, v75
	ds_bpermute_b32 v114, v77, v74
	v_lshl_add_u64 v[116:117], v[42:43], 0, v[54:55]
	global_store_dwordx2 v[116:117], v[90:91], off nt
	global_store_dwordx2 v[116:117], v[92:93], off offset:512 nt
	v_lshl_add_u64 v[54:55], v[44:45], 0, v[54:55]
	global_store_dwordx2 v[116:117], v[94:95], off offset:1024 nt
	global_store_dwordx2 v[116:117], v[96:97], off offset:1536 nt
	s_waitcnt lgkmcnt(0)
	v_pk_add_f32 v[74:75], v[74:75], v[114:115]
	ds_bpermute_b32 v115, v78, v75
	ds_bpermute_b32 v114, v78, v74
	s_waitcnt lgkmcnt(0)
	v_pk_add_f32 v[74:75], v[74:75], v[114:115]
	ds_bpermute_b32 v115, v79, v75
	ds_bpermute_b32 v114, v79, v74
	s_waitcnt lgkmcnt(0)
	v_pk_add_f32 v[74:75], v[74:75], v[114:115]
	ds_bpermute_b32 v115, v80, v75
	ds_bpermute_b32 v114, v80, v74
	s_waitcnt lgkmcnt(0)
	v_pk_add_f32 v[74:75], v[74:75], v[114:115]
	s_nop 0
	v_pk_fma_f32 v[74:75], v[74:75], s[0:1], v[50:51] op_sel_hi:[1,0,0]
	s_nop 0
	v_mul_f32_e32 v49, 0x4b800000, v75
	v_cmp_gt_f32_e32 vcc, s6, v75
	s_nop 1
	v_cndmask_b32_e32 v49, v75, v49, vcc
	v_rsq_f32_e32 v49, v49
	s_nop 0
	v_mul_f32_e32 v58, 0x45800000, v49
	v_cndmask_b32_e32 v58, v49, v58, vcc
	v_mul_f32_e32 v49, 0x4b800000, v74
	v_cmp_gt_f32_e32 vcc, s6, v74
	v_pk_mul_f32 v[90:91], v[58:59], v[100:101] op_sel_hi:[0,1]
	v_pk_mul_f32 v[92:93], v[58:59], v[98:99] op_sel_hi:[0,1]
	v_cndmask_b32_e32 v49, v74, v49, vcc
	v_rsq_f32_e32 v49, v49
	v_pk_mul_f32 v[90:91], v[28:29], v[90:91]
	v_pk_mul_f32 v[74:75], v[30:31], v[92:93]
	v_cvt_pk_bf16_f32 v90, v90, v91
	v_mul_f32_e32 v60, 0x45800000, v49
	v_cvt_pk_bf16_f32 v91, v74, v75
	v_cndmask_b32_e32 v74, v49, v60, vcc
	global_store_dwordx2 v[54:55], v[90:91], off nt
	v_pk_mul_f32 v[90:91], v[74:75], v[102:103] op_sel_hi:[0,1]
	v_pk_mul_f32 v[92:93], v[74:75], v[104:105] op_sel_hi:[0,1]
	s_waitcnt vmcnt(8)
	v_pk_fma_f32 v[38:39], v[2:3], v[92:93], v[38:39]
	v_pk_fma_f32 v[36:37], v[0:1], v[90:91], v[36:37]
	v_mov_b32_e32 v60, v59
	v_cvt_pk_bf16_f32 v36, v36, v37
	v_cvt_pk_bf16_f32 v37, v38, v39
	v_mov_b32_e32 v38, v106
	v_mov_b32_e32 v39, v108
	v_mov_b32_e32 v108, v107
	v_pk_mul_f32 v[38:39], v[74:75], v[38:39] op_sel_hi:[0,1]
	v_pk_mul_f32 v[90:91], v[74:75], v[108:109] op_sel_hi:[0,1]
	s_waitcnt vmcnt(7)
	v_pk_fma_f32 v[34:35], v[6:7], v[90:91], v[34:35]
	v_pk_fma_f32 v[32:33], v[4:5], v[38:39], v[32:33]
	v_pk_mul_f32 v[38:39], v[74:75], v[110:111] op_sel_hi:[0,1]
	v_cvt_pk_bf16_f32 v32, v32, v33
	v_cvt_pk_bf16_f32 v33, v34, v35
	v_pk_mul_f32 v[34:35], v[74:75], v[112:113] op_sel_hi:[0,1]
	s_waitcnt vmcnt(6)
; __device__ __forceinline__ unsigned pk_bf16(float lo, float hi) { const f32x2 v = {lo, hi}; return __builtin_bit_cast(unsigned, __builtin_convertvector(v, b16x2)); }
;     __device__ __forceinline__ void row(int r, int col32, int fq, const f32x4& a00, const f32x4& a01, const f32x4& a10, const f32x4& a11) const { half(r, col32, fq, a00, a01); half(r, col32 + HALF, fq, a10, a11); }
;     __device__ __forceinline__ void row(int r, int col32, int fq, const f32x4& a00, const f32x4& a01, const f32x4& a10, const f32x4& a11) const { half(r, col32, fq, a00, a01); half(r, col32 + HALF, fq, a10, a11); }
;     __device__ __forceinline__ void row(int r, int col32, int fq, const f32x4& a00, const f32x4& a01, const f32x4& a10, const f32x4& a11) const { half(r, col32, fq, a00, a01); half(r, col32 + HALF, fq, a10, a11); }
; __device__ __forceinline__ void phase6(const Params& p) {
;     ...
;             float s2 = 0.f;
; #pragma unroll
;             for (int j = 0; j < 4; ++j) {
;                 v[r][j] = x[r][j] + v[r][j] * rs * g1[j];
;                 { u32x2 hb; hb.x = pk_bf16(v[r][j][0], v[r][j][1]); hb.y = pk_bf16(v[r][j][2], v[r][j][3]);
;                   *(u32x2*)((bf16_t*)(ws + O_H1B) + (size_t)row * D + 4 * lane + 256 * j) = hb;
;                   v[r][j] = (f32x4){__uint_as_float(hb.x << 16), __uint_as_float(hb.x & 0xffff0000u), __uint_as_float(hb.y << 16), __uint_as_float(hb.y & 0xffff0000u)}; }
;                 s2 += (v[r][j][0] * v[r][j][0] + v[r][j][1] * v[r][j][1]) + (v[r][j][2] * v[r][j][2] + v[r][j][3] * v[r][j][3]);
;             }
;             const float rs2 = rsqrtf(wave_sum(s2) * (1.0f / D) + RMS_EPS);
;             bf16_t* fr_ = (bf16_t*)(ws + O_F) + (size_t)row * D;
; #pragma unroll
;             for (int j = 0; j < 4; ++j) {
;                 u32x2 w; w.x = pk_bf16(v[r][j][0] * rs2 * g2[j][0], v[r][j][1] * rs2 * g2[j][1]); w.y = pk_bf16(v[r][j][2] * rs2 * g2[j][2], v[r][j][3] * rs2 * g2[j][3]);
;                 *(u32x2*)(fr_ + 4 * lane + 256 * j) = w;
;             }
;         }
	v_pk_fma_f32 v[38:39], v[10:11], v[38:39], v[84:85]
	v_pk_fma_f32 v[34:35], v[8:9], v[34:35], v[82:83]
	v_pk_mul_f32 v[56:57], v[74:75], v[56:57] op_sel_hi:[0,1]
	v_cvt_pk_bf16_f32 v34, v34, v35
	v_cvt_pk_bf16_f32 v35, v38, v39
	v_pk_mul_f32 v[38:39], v[74:75], v[60:61] op_sel_hi:[0,1]
	s_waitcnt vmcnt(5)
	v_pk_fma_f32 v[56:57], v[14:15], v[56:57], v[88:89]
	v_pk_fma_f32 v[38:39], v[12:13], v[38:39], v[86:87]
	v_and_b32_e32 v61, 0xffff0000, v36
	v_cvt_pk_bf16_f32 v38, v38, v39
	v_cvt_pk_bf16_f32 v39, v56, v57
	v_and_b32_e32 v57, 0xffff0000, v37
	v_lshlrev_b32_e32 v56, 16, v37
	v_lshlrev_b32_e32 v60, 16, v36
	v_mov_b32_e32 v82, v61
	v_mov_b32_e32 v83, v57
	v_mov_b32_e32 v74, v60
	v_mov_b32_e32 v75, v56
	v_pk_mul_f32 v[82:83], v[82:83], v[82:83]
	v_and_b32_e32 v85, 0xffff0000, v32
	v_pk_fma_f32 v[74:75], v[74:75], v[74:75], v[82:83]
	v_and_b32_e32 v83, 0xffff0000, v33
	v_lshlrev_b32_e32 v82, 16, v33
	v_lshlrev_b32_e32 v84, 16, v32
	v_mov_b32_e32 v88, v85
	v_mov_b32_e32 v89, v83
	v_mov_b32_e32 v86, v84
	v_mov_b32_e32 v87, v82
	v_pk_mul_f32 v[88:89], v[88:89], v[88:89]
	v_pk_add_f32 v[74:75], v[74:75], v[74:75] op_sel_hi:[0,1]
	v_pk_fma_f32 v[86:87], v[86:87], v[86:87], v[88:89]
	v_lshlrev_b32_e32 v88, 16, v35
	v_and_b32_e32 v89, 0xffff0000, v35
	v_mul_f32_e32 v74, v88, v88
	v_lshlrev_b32_e32 v92, 16, v34
	v_pk_fma_f32 v[90:91], v[88:89], v[88:89], v[74:75] op_sel_hi:[1,1,0]
	v_and_b32_e32 v93, 0xffff0000, v34
	v_mul_f32_e32 v74, v92, v92
	v_lshlrev_b32_e32 v96, 16, v39
	v_and_b32_e32 v97, 0xffff0000, v39
	v_lshlrev_b32_e32 v100, 16, v38
	v_and_b32_e32 v101, 0xffff0000, v38
	v_pk_add_f32 v[86:87], v[86:87], v[86:87] op_sel_hi:[0,1]
	v_pk_fma_f32 v[94:95], v[92:93], v[92:93], v[74:75] op_sel_hi:[1,1,0]
	v_pk_mul_f32 v[98:99], v[96:97], v[96:97]
	v_pk_mul_f32 v[102:103], v[100:101], v[100:101]
	v_mov_b32_e32 v74, v98
	v_mov_b32_e32 v86, v99
	v_mov_b32_e32 v94, v102
	v_mov_b32_e32 v90, v103
	v_pk_add_f32 v[74:75], v[74:75], v[86:87]
	v_pk_add_f32 v[86:87], v[94:95], v[90:91]
	s_nop 0
	v_pk_add_f32 v[74:75], v[86:87], v[74:75]
	s_nop 0
	v_add_f32_e32 v49, v74, v75
	ds_bpermute_b32 v59, v51, v49
	s_waitcnt lgkmcnt(0)
	v_add_f32_e32 v49, v49, v59
	v_pk_mul_f32 v[66:67], v[58:59], v[66:67] op_sel_hi:[0,1]
	v_pk_mul_f32 v[62:63], v[58:59], v[62:63] op_sel_hi:[0,1]
	ds_bpermute_b32 v59, v76, v49
	v_pk_mul_f32 v[66:67], v[24:25], v[66:67]
	v_pk_mul_f32 v[62:63], v[26:27], v[62:63]
	v_cvt_pk_bf16_f32 v66, v66, v67
	v_cvt_pk_bf16_f32 v67, v62, v63
	s_waitcnt lgkmcnt(0)
	v_add_f32_e32 v49, v49, v59
	v_pk_mul_f32 v[62:63], v[58:59], v[70:71] op_sel_hi:[0,1]
	ds_bpermute_b32 v59, v77, v49
	v_pk_mul_f32 v[62:63], v[20:21], v[62:63]
	global_store_dwordx2 v[54:55], v[66:67], off offset:512 nt
	v_cvt_pk_bf16_f32 v62, v62, v63
	s_waitcnt lgkmcnt(0)
	v_add_f32_e32 v49, v49, v59
	v_pk_mul_f32 v[64:65], v[58:59], v[64:65] op_sel_hi:[0,1]
	ds_bpermute_b32 v59, v78, v49
	v_pk_mul_f32 v[64:65], v[22:23], v[64:65]
	s_waitcnt lgkmcnt(0)
	v_add_f32_e32 v49, v49, v59
	v_cvt_pk_bf16_f32 v63, v64, v65
	ds_bpermute_b32 v64, v79, v49
	global_store_dwordx2 v[54:55], v[62:63], off offset:1024 nt
	v_pk_mul_f32 v[62:63], v[58:59], v[72:73] op_sel_hi:[0,1]
	v_pk_mul_f32 v[58:59], v[58:59], v[68:69] op_sel_hi:[0,1]
	v_pk_mul_f32 v[62:63], v[16:17], v[62:63]
	v_pk_mul_f32 v[58:59], v[18:19], v[58:59]
	s_waitcnt lgkmcnt(0)
	v_add_f32_e32 v49, v49, v64
	v_cvt_pk_bf16_f32 v62, v62, v63
	v_cvt_pk_bf16_f32 v63, v58, v59
	ds_bpermute_b32 v58, v80, v49
	global_store_dwordx2 v[54:55], v[62:63], off offset:1536 nt
	v_lshl_add_u64 v[54:55], v[42:43], 0, v[52:53]
	global_store_dwordx2 v[54:55], v[36:37], off nt
	global_store_dwordx2 v[54:55], v[32:33], off offset:512 nt
	global_store_dwordx2 v[54:55], v[34:35], off offset:1024 nt
	global_store_dwordx2 v[54:55], v[38:39], off offset:1536 nt
	s_waitcnt lgkmcnt(0)
	v_add_f32_e32 v32, v49, v58
	v_fmamk_f32 v32, v32, 0x3a800000, v50
	v_mul_f32_e32 v33, 0x4b800000, v32
	v_cmp_gt_f32_e32 vcc, s6, v32
	s_nop 1
	v_cndmask_b32_e32 v32, v32, v33, vcc
	v_rsq_f32_e32 v36, v32
	v_lshl_add_u64 v[32:33], v[44:45], 0, v[52:53]
	v_mul_f32_e32 v34, 0x45800000, v36
	v_cndmask_b32_e32 v34, v36, v34, vcc
	v_pk_mul_f32 v[36:37], v[34:35], v[60:61] op_sel_hi:[0,1]
	v_pk_mul_f32 v[38:39], v[34:35], v[56:57] op_sel_hi:[0,1]
	v_pk_mul_f32 v[36:37], v[28:29], v[36:37]
	v_pk_mul_f32 v[38:39], v[30:31], v[38:39]
	v_cvt_pk_bf16_f32 v36, v36, v37
	v_cvt_pk_bf16_f32 v37, v38, v39
	global_store_dwordx2 v[32:33], v[36:37], off nt
	v_pk_mul_f32 v[36:37], v[34:35], v[84:85] op_sel_hi:[0,1]
	v_pk_mul_f32 v[38:39], v[34:35], v[82:83] op_sel_hi:[0,1]
	v_pk_mul_f32 v[36:37], v[24:25], v[36:37]
	v_pk_mul_f32 v[38:39], v[26:27], v[38:39]
	v_cvt_pk_bf16_f32 v36, v36, v37
	v_cvt_pk_bf16_f32 v37, v38, v39
	global_store_dwordx2 v[32:33], v[36:37], off offset:512 nt
	v_pk_mul_f32 v[36:37], v[34:35], v[92:93] op_sel_hi:[0,1]
	v_pk_mul_f32 v[38:39], v[34:35], v[88:89] op_sel_hi:[0,1]
	v_pk_mul_f32 v[36:37], v[20:21], v[36:37]
	v_pk_mul_f32 v[38:39], v[22:23], v[38:39]
	v_cvt_pk_bf16_f32 v36, v36, v37
	v_cvt_pk_bf16_f32 v37, v38, v39
	global_store_dwordx2 v[32:33], v[36:37], off offset:1024 nt
	v_pk_mul_f32 v[36:37], v[34:35], v[100:101] op_sel_hi:[0,1]
	v_pk_mul_f32 v[34:35], v[34:35], v[96:97] op_sel_hi:[0,1]
	v_pk_mul_f32 v[36:37], v[16:17], v[36:37]
	v_pk_mul_f32 v[34:35], v[18:19], v[34:35]
	v_cvt_pk_bf16_f32 v36, v36, v37
	v_cvt_pk_bf16_f32 v37, v34, v35
	global_store_dwordx2 v[32:33], v[36:37], off offset:1536 nt
	s_cbranch_scc1 .LBB0_1184
